# FF1 squared-ReLU epilogue as one contiguous sixteen-block sequence at the head of the tile epilogue
# speedup vs baseline: 1.0040x; 1.0004x over previous
.LBB0_90:
	v_mov_b32_e32 v136, s88
	ds_read_b32 v136, v136
	v_readlane_b32 s2, v254, 44
	v_mov_b32_e32 v151, v153
	s_mov_b64 s[58:59], -1
	s_mov_b64 s[56:57], 0
	s_waitcnt lgkmcnt(0)
	v_readfirstlane_b32 s48, v136
	v_mov_b32_e32 v136, s89
	ds_read_b32 v136, v136
	s_add_u32 s52, s48, 0x2100000
	s_waitcnt lgkmcnt(0)
	v_readfirstlane_b32 s49, v136
	v_mov_b32_e32 v136, s2
	ds_read_b32 v136, v136
	v_readlane_b32 s2, v254, 45
	s_addc_u32 s53, s49, 0
	s_add_u32 s46, s48, 0x158d0000
	s_addc_u32 s47, s49, 0
	s_waitcnt lgkmcnt(0)
	v_readfirstlane_b32 s42, v136
	v_mov_b32_e32 v136, s2
	ds_read_b32 v136, v136
	v_readlane_b32 s2, v254, 31
	s_add_u32 s40, s48, 0xc600000
	s_addc_u32 s41, s49, 0
	s_add_u32 s36, s48, 0xe700000
	s_waitcnt lgkmcnt(0)
	v_readfirstlane_b32 s43, v136
	v_mov_b32_e32 v136, s2
	ds_read_b32 v136, v136
	v_readlane_b32 s2, v254, 46
	s_addc_u32 s37, s49, 0
	s_add_u32 s34, s48, 0x6300000
	s_addc_u32 s35, s49, 0
	s_waitcnt lgkmcnt(0)
	v_readfirstlane_b32 s65, v136
	v_mov_b32_e32 v136, s2
	ds_read_b32 v136, v136
	v_readlane_b32 s2, v254, 39
	s_add_u32 s38, s48, 0x4200000
	s_addc_u32 s39, s49, 0
	s_add_u32 s50, s48, 0x15af4000
	s_waitcnt lgkmcnt(0)
	v_readfirstlane_b32 s66, v136
	v_mov_b32_e32 v136, s2
	ds_read_b32 v136, v136
	v_readlane_b32 s2, v254, 48
	s_addc_u32 s51, s49, 0
	s_lshl_b32 s62, s10, 8
	s_lshl_b32 s27, s67, 8
	s_waitcnt lgkmcnt(0)
	v_readfirstlane_b32 s44, v136
	v_mov_b32_e32 v136, s2
	v_readlane_b32 s2, v254, 40
	s_add_i32 s62, s62, s2
	s_ashr_i32 s2, s62, 13
	ds_read_b32 v136, v136
	s_mul_i32 s54, s2, 0x1800
	v_readlane_b32 s2, v254, 26
	s_ashr_i32 s55, s54, 31
	s_mul_i32 s2, s2, 0x12000
	s_add_u32 s2, s48, s2
	v_or_b32_e32 v138, s62, v157
	s_addc_u32 s3, s49, 0
	v_ashrrev_i32_e32 v139, 31, v138
	s_add_u32 s30, s2, 0x15ad0000
	s_waitcnt lgkmcnt(0)
	v_readfirstlane_b32 s45, v136
	v_lshlrev_b64 v[136:137], 13, v[138:139]
	v_add_u32_e32 v150, 0xffffc000, v138
	s_addc_u32 s31, s3, 0
	v_lshl_add_u64 v[148:149], s[52:53], 0, v[136:137]
	v_cmp_gt_i32_e64 s[10:11], s92, v138
	v_cmp_lt_i32_e64 s[8:9], s80, v138
	v_lshlrev_b64 v[146:147], 10, v[150:151]
	v_lshlrev_b64 v[142:143], 10, v[138:139]
	v_or_b32_e32 v136, s27, v161
	s_cmp_lg_u32 s79, 26
	s_cbranch_scc1 .Lff1_no
	v_ashrrev_i32_e32 v137, 31, v136
	v_lshl_add_u64 v[244:245], v[136:137], 1, v[148:149]
	v_max_f32_e32 v230, v124, v124
	v_max_f32_e32 v230, 0, v230
	v_mul_f32_e32 v230, v230, v230
	v_max_f32_e32 v231, v125, v125
	v_max_f32_e32 v231, 0, v231
	v_mul_f32_e32 v231, v231, v231
	v_max_f32_e32 v232, v126, v126
	v_max_f32_e32 v232, 0, v232
	v_mul_f32_e32 v232, v232, v232
	v_max_f32_e32 v233, v127, v127
	v_max_f32_e32 v233, 0, v233
	v_mul_f32_e32 v233, v233, v233
	v_max_f32_e32 v234, v120, v120
	v_max_f32_e32 v234, 0, v234
	v_mul_f32_e32 v234, v234, v234
	v_max_f32_e32 v235, v121, v121
	v_max_f32_e32 v235, 0, v235
	v_mul_f32_e32 v235, v235, v235
	v_max_f32_e32 v236, v122, v122
	v_max_f32_e32 v236, 0, v236
	v_mul_f32_e32 v236, v236, v236
	v_max_f32_e32 v237, v123, v123
	v_max_f32_e32 v237, 0, v237
	v_mul_f32_e32 v237, v237, v237
	v_cvt_pk_bf16_f32 v230, v230, v231
	v_cvt_pk_bf16_f32 v231, v232, v233
	v_cvt_pk_bf16_f32 v234, v234, v235
	v_cvt_pk_bf16_f32 v235, v236, v237
	global_store_dwordx2 v[244:245], v[230:231], off
	global_store_dwordx2 v[244:245], v[234:235], off offset:32
	v_max_f32_e32 v230, v116, v116
	v_max_f32_e32 v230, 0, v230
	v_mul_f32_e32 v230, v230, v230
	v_max_f32_e32 v231, v117, v117
	v_max_f32_e32 v231, 0, v231
	v_mul_f32_e32 v231, v231, v231
	v_max_f32_e32 v232, v118, v118
	v_max_f32_e32 v232, 0, v232
	v_mul_f32_e32 v232, v232, v232
	v_max_f32_e32 v233, v119, v119
	v_max_f32_e32 v233, 0, v233
	v_mul_f32_e32 v233, v233, v233
	v_max_f32_e32 v234, v112, v112
	v_max_f32_e32 v234, 0, v234
	v_mul_f32_e32 v234, v234, v234
	v_max_f32_e32 v235, v113, v113
	v_max_f32_e32 v235, 0, v235
	v_mul_f32_e32 v235, v235, v235
	v_max_f32_e32 v236, v114, v114
	v_max_f32_e32 v236, 0, v236
	v_mul_f32_e32 v236, v236, v236
	v_max_f32_e32 v237, v115, v115
	v_max_f32_e32 v237, 0, v237
	v_mul_f32_e32 v237, v237, v237
	v_cvt_pk_bf16_f32 v230, v230, v231
	v_cvt_pk_bf16_f32 v231, v232, v233
	v_cvt_pk_bf16_f32 v234, v234, v235
	v_cvt_pk_bf16_f32 v235, v236, v237
	v_add_co_u32_e32 v246, vcc, 0x100, v244
	v_addc_co_u32_e32 v247, vcc, 0, v245, vcc
	global_store_dwordx2 v[246:247], v[230:231], off
	global_store_dwordx2 v[246:247], v[234:235], off offset:32
	v_max_f32_e32 v230, v108, v108
	v_max_f32_e32 v230, 0, v230
	v_mul_f32_e32 v230, v230, v230
	v_max_f32_e32 v231, v109, v109
	v_max_f32_e32 v231, 0, v231
	v_mul_f32_e32 v231, v231, v231
	v_max_f32_e32 v232, v110, v110
	v_max_f32_e32 v232, 0, v232
	v_mul_f32_e32 v232, v232, v232
	v_max_f32_e32 v233, v111, v111
	v_max_f32_e32 v233, 0, v233
	v_mul_f32_e32 v233, v233, v233
	v_max_f32_e32 v234, v104, v104
	v_max_f32_e32 v234, 0, v234
	v_mul_f32_e32 v234, v234, v234
	v_max_f32_e32 v235, v105, v105
	v_max_f32_e32 v235, 0, v235
	v_mul_f32_e32 v235, v235, v235
	v_max_f32_e32 v236, v106, v106
	v_max_f32_e32 v236, 0, v236
	v_mul_f32_e32 v236, v236, v236
	v_max_f32_e32 v237, v107, v107
	v_max_f32_e32 v237, 0, v237
	v_mul_f32_e32 v237, v237, v237
	v_cvt_pk_bf16_f32 v230, v230, v231
	v_cvt_pk_bf16_f32 v231, v232, v233
	v_cvt_pk_bf16_f32 v234, v234, v235
	v_cvt_pk_bf16_f32 v235, v236, v237
	v_add_co_u32_e32 v246, vcc, 0x20000, v244
	v_addc_co_u32_e32 v247, vcc, 0, v245, vcc
	global_store_dwordx2 v[246:247], v[230:231], off
	global_store_dwordx2 v[246:247], v[234:235], off offset:32
	v_max_f32_e32 v230, v100, v100
	v_max_f32_e32 v230, 0, v230
	v_mul_f32_e32 v230, v230, v230
	v_max_f32_e32 v231, v101, v101
	v_max_f32_e32 v231, 0, v231
	v_mul_f32_e32 v231, v231, v231
	v_max_f32_e32 v232, v102, v102
	v_max_f32_e32 v232, 0, v232
	v_mul_f32_e32 v232, v232, v232
	v_max_f32_e32 v233, v103, v103
	v_max_f32_e32 v233, 0, v233
	v_mul_f32_e32 v233, v233, v233
	v_max_f32_e32 v234, v96, v96
	v_max_f32_e32 v234, 0, v234
	v_mul_f32_e32 v234, v234, v234
	v_max_f32_e32 v235, v97, v97
	v_max_f32_e32 v235, 0, v235
	v_mul_f32_e32 v235, v235, v235
	v_max_f32_e32 v236, v98, v98
	v_max_f32_e32 v236, 0, v236
	v_mul_f32_e32 v236, v236, v236
	v_max_f32_e32 v237, v99, v99
	v_max_f32_e32 v237, 0, v237
	v_mul_f32_e32 v237, v237, v237
	v_cvt_pk_bf16_f32 v230, v230, v231
	v_cvt_pk_bf16_f32 v231, v232, v233
	v_cvt_pk_bf16_f32 v234, v234, v235
	v_cvt_pk_bf16_f32 v235, v236, v237
	v_add_co_u32_e32 v246, vcc, 0x20100, v244
	v_addc_co_u32_e32 v247, vcc, 0, v245, vcc
	global_store_dwordx2 v[246:247], v[230:231], off
	global_store_dwordx2 v[246:247], v[234:235], off offset:32
	v_max_f32_e32 v230, v92, v92
	v_max_f32_e32 v230, 0, v230
	v_mul_f32_e32 v230, v230, v230
	v_max_f32_e32 v231, v93, v93
	v_max_f32_e32 v231, 0, v231
	v_mul_f32_e32 v231, v231, v231
	v_max_f32_e32 v232, v94, v94
	v_max_f32_e32 v232, 0, v232
	v_mul_f32_e32 v232, v232, v232
	v_max_f32_e32 v233, v95, v95
	v_max_f32_e32 v233, 0, v233
	v_mul_f32_e32 v233, v233, v233
	v_max_f32_e32 v234, v88, v88
	v_max_f32_e32 v234, 0, v234
	v_mul_f32_e32 v234, v234, v234
	v_max_f32_e32 v235, v89, v89
	v_max_f32_e32 v235, 0, v235
	v_mul_f32_e32 v235, v235, v235
	v_max_f32_e32 v236, v90, v90
	v_max_f32_e32 v236, 0, v236
	v_mul_f32_e32 v236, v236, v236
	v_max_f32_e32 v237, v91, v91
	v_max_f32_e32 v237, 0, v237
	v_mul_f32_e32 v237, v237, v237
	v_cvt_pk_bf16_f32 v230, v230, v231
	v_cvt_pk_bf16_f32 v231, v232, v233
	v_cvt_pk_bf16_f32 v234, v234, v235
	v_cvt_pk_bf16_f32 v235, v236, v237
	v_add_co_u32_e32 v246, vcc, 0x40000, v244
	v_addc_co_u32_e32 v247, vcc, 0, v245, vcc
	global_store_dwordx2 v[246:247], v[230:231], off
	global_store_dwordx2 v[246:247], v[234:235], off offset:32
	v_max_f32_e32 v230, v84, v84
	v_max_f32_e32 v230, 0, v230
	v_mul_f32_e32 v230, v230, v230
	v_max_f32_e32 v231, v85, v85
	v_max_f32_e32 v231, 0, v231
	v_mul_f32_e32 v231, v231, v231
	v_max_f32_e32 v232, v86, v86
	v_max_f32_e32 v232, 0, v232
	v_mul_f32_e32 v232, v232, v232
	v_max_f32_e32 v233, v87, v87
	v_max_f32_e32 v233, 0, v233
	v_mul_f32_e32 v233, v233, v233
	v_max_f32_e32 v234, v80, v80
	v_max_f32_e32 v234, 0, v234
	v_mul_f32_e32 v234, v234, v234
	v_max_f32_e32 v235, v81, v81
	v_max_f32_e32 v235, 0, v235
	v_mul_f32_e32 v235, v235, v235
	v_max_f32_e32 v236, v82, v82
	v_max_f32_e32 v236, 0, v236
	v_mul_f32_e32 v236, v236, v236
	v_max_f32_e32 v237, v83, v83
	v_max_f32_e32 v237, 0, v237
	v_mul_f32_e32 v237, v237, v237
	v_cvt_pk_bf16_f32 v230, v230, v231
	v_cvt_pk_bf16_f32 v231, v232, v233
	v_cvt_pk_bf16_f32 v234, v234, v235
	v_cvt_pk_bf16_f32 v235, v236, v237
	v_add_co_u32_e32 v246, vcc, 0x40100, v244
	v_addc_co_u32_e32 v247, vcc, 0, v245, vcc
	global_store_dwordx2 v[246:247], v[230:231], off
	global_store_dwordx2 v[246:247], v[234:235], off offset:32
	v_max_f32_e32 v230, v76, v76
	v_max_f32_e32 v230, 0, v230
	v_mul_f32_e32 v230, v230, v230
	v_max_f32_e32 v231, v77, v77
	v_max_f32_e32 v231, 0, v231
	v_mul_f32_e32 v231, v231, v231
	v_max_f32_e32 v232, v78, v78
	v_max_f32_e32 v232, 0, v232
	v_mul_f32_e32 v232, v232, v232
	v_max_f32_e32 v233, v79, v79
	v_max_f32_e32 v233, 0, v233
	v_mul_f32_e32 v233, v233, v233
	v_max_f32_e32 v234, v72, v72
	v_max_f32_e32 v234, 0, v234
	v_mul_f32_e32 v234, v234, v234
	v_max_f32_e32 v235, v73, v73
	v_max_f32_e32 v235, 0, v235
	v_mul_f32_e32 v235, v235, v235
	v_max_f32_e32 v236, v74, v74
	v_max_f32_e32 v236, 0, v236
	v_mul_f32_e32 v236, v236, v236
	v_max_f32_e32 v237, v75, v75
	v_max_f32_e32 v237, 0, v237
	v_mul_f32_e32 v237, v237, v237
	v_cvt_pk_bf16_f32 v230, v230, v231
	v_cvt_pk_bf16_f32 v231, v232, v233
	v_cvt_pk_bf16_f32 v234, v234, v235
	v_cvt_pk_bf16_f32 v235, v236, v237
	v_add_co_u32_e32 v246, vcc, 0x60000, v244
	v_addc_co_u32_e32 v247, vcc, 0, v245, vcc
	global_store_dwordx2 v[246:247], v[230:231], off
	global_store_dwordx2 v[246:247], v[234:235], off offset:32
	v_max_f32_e32 v230, v68, v68
	v_max_f32_e32 v230, 0, v230
	v_mul_f32_e32 v230, v230, v230
	v_max_f32_e32 v231, v69, v69
	v_max_f32_e32 v231, 0, v231
	v_mul_f32_e32 v231, v231, v231
	v_max_f32_e32 v232, v70, v70
	v_max_f32_e32 v232, 0, v232
	v_mul_f32_e32 v232, v232, v232
	v_max_f32_e32 v233, v71, v71
	v_max_f32_e32 v233, 0, v233
	v_mul_f32_e32 v233, v233, v233
	v_max_f32_e32 v234, v64, v64
	v_max_f32_e32 v234, 0, v234
	v_mul_f32_e32 v234, v234, v234
	v_max_f32_e32 v235, v65, v65
	v_max_f32_e32 v235, 0, v235
	v_mul_f32_e32 v235, v235, v235
	v_max_f32_e32 v236, v66, v66
	v_max_f32_e32 v236, 0, v236
	v_mul_f32_e32 v236, v236, v236
	v_max_f32_e32 v237, v67, v67
	v_max_f32_e32 v237, 0, v237
	v_mul_f32_e32 v237, v237, v237
	v_cvt_pk_bf16_f32 v230, v230, v231
	v_cvt_pk_bf16_f32 v231, v232, v233
	v_cvt_pk_bf16_f32 v234, v234, v235
	v_cvt_pk_bf16_f32 v235, v236, v237
	v_add_co_u32_e32 v246, vcc, 0x60100, v244
	v_addc_co_u32_e32 v247, vcc, 0, v245, vcc
	global_store_dwordx2 v[246:247], v[230:231], off
	global_store_dwordx2 v[246:247], v[234:235], off offset:32
	v_max_f32_e32 v230, v60, v60
	v_max_f32_e32 v230, 0, v230
	v_mul_f32_e32 v230, v230, v230
	v_max_f32_e32 v231, v61, v61
	v_max_f32_e32 v231, 0, v231
	v_mul_f32_e32 v231, v231, v231
	v_max_f32_e32 v232, v62, v62
	v_max_f32_e32 v232, 0, v232
	v_mul_f32_e32 v232, v232, v232
	v_max_f32_e32 v233, v63, v63
	v_max_f32_e32 v233, 0, v233
	v_mul_f32_e32 v233, v233, v233
	v_max_f32_e32 v234, v56, v56
	v_max_f32_e32 v234, 0, v234
	v_mul_f32_e32 v234, v234, v234
	v_max_f32_e32 v235, v57, v57
	v_max_f32_e32 v235, 0, v235
	v_mul_f32_e32 v235, v235, v235
	v_max_f32_e32 v236, v58, v58
	v_max_f32_e32 v236, 0, v236
	v_mul_f32_e32 v236, v236, v236
	v_max_f32_e32 v237, v59, v59
	v_max_f32_e32 v237, 0, v237
	v_mul_f32_e32 v237, v237, v237
	v_cvt_pk_bf16_f32 v230, v230, v231
	v_cvt_pk_bf16_f32 v231, v232, v233
	v_cvt_pk_bf16_f32 v234, v234, v235
	v_cvt_pk_bf16_f32 v235, v236, v237
	v_add_co_u32_e32 v246, vcc, 0x100000, v244
	v_addc_co_u32_e32 v247, vcc, 0, v245, vcc
	global_store_dwordx2 v[246:247], v[230:231], off
	global_store_dwordx2 v[246:247], v[234:235], off offset:32
	v_max_f32_e32 v230, v52, v52
	v_max_f32_e32 v230, 0, v230
	v_mul_f32_e32 v230, v230, v230
	v_max_f32_e32 v231, v53, v53
	v_max_f32_e32 v231, 0, v231
	v_mul_f32_e32 v231, v231, v231
	v_max_f32_e32 v232, v54, v54
	v_max_f32_e32 v232, 0, v232
	v_mul_f32_e32 v232, v232, v232
	v_max_f32_e32 v233, v55, v55
	v_max_f32_e32 v233, 0, v233
	v_mul_f32_e32 v233, v233, v233
	v_max_f32_e32 v234, v48, v48
	v_max_f32_e32 v234, 0, v234
	v_mul_f32_e32 v234, v234, v234
	v_max_f32_e32 v235, v49, v49
	v_max_f32_e32 v235, 0, v235
	v_mul_f32_e32 v235, v235, v235
	v_max_f32_e32 v236, v50, v50
	v_max_f32_e32 v236, 0, v236
	v_mul_f32_e32 v236, v236, v236
	v_max_f32_e32 v237, v51, v51
	v_max_f32_e32 v237, 0, v237
	v_mul_f32_e32 v237, v237, v237
	v_cvt_pk_bf16_f32 v230, v230, v231
	v_cvt_pk_bf16_f32 v231, v232, v233
	v_cvt_pk_bf16_f32 v234, v234, v235
	v_cvt_pk_bf16_f32 v235, v236, v237
	v_add_co_u32_e32 v246, vcc, 0x100100, v244
	v_addc_co_u32_e32 v247, vcc, 0, v245, vcc
	global_store_dwordx2 v[246:247], v[230:231], off
	global_store_dwordx2 v[246:247], v[234:235], off offset:32
	v_max_f32_e32 v230, v44, v44
	v_max_f32_e32 v230, 0, v230
	v_mul_f32_e32 v230, v230, v230
	v_max_f32_e32 v231, v45, v45
	v_max_f32_e32 v231, 0, v231
	v_mul_f32_e32 v231, v231, v231
	v_max_f32_e32 v232, v46, v46
	v_max_f32_e32 v232, 0, v232
	v_mul_f32_e32 v232, v232, v232
	v_max_f32_e32 v233, v47, v47
	v_max_f32_e32 v233, 0, v233
	v_mul_f32_e32 v233, v233, v233
	v_max_f32_e32 v234, v40, v40
	v_max_f32_e32 v234, 0, v234
	v_mul_f32_e32 v234, v234, v234
	v_max_f32_e32 v235, v41, v41
	v_max_f32_e32 v235, 0, v235
	v_mul_f32_e32 v235, v235, v235
	v_max_f32_e32 v236, v42, v42
	v_max_f32_e32 v236, 0, v236
	v_mul_f32_e32 v236, v236, v236
	v_max_f32_e32 v237, v43, v43
	v_max_f32_e32 v237, 0, v237
	v_mul_f32_e32 v237, v237, v237
	v_cvt_pk_bf16_f32 v230, v230, v231
	v_cvt_pk_bf16_f32 v231, v232, v233
	v_cvt_pk_bf16_f32 v234, v234, v235
	v_cvt_pk_bf16_f32 v235, v236, v237
	v_add_co_u32_e32 v246, vcc, 0x120000, v244
	v_addc_co_u32_e32 v247, vcc, 0, v245, vcc
	global_store_dwordx2 v[246:247], v[230:231], off
	global_store_dwordx2 v[246:247], v[234:235], off offset:32
	v_max_f32_e32 v230, v36, v36
	v_max_f32_e32 v230, 0, v230
	v_mul_f32_e32 v230, v230, v230
	v_max_f32_e32 v231, v37, v37
	v_max_f32_e32 v231, 0, v231
	v_mul_f32_e32 v231, v231, v231
	v_max_f32_e32 v232, v38, v38
	v_max_f32_e32 v232, 0, v232
	v_mul_f32_e32 v232, v232, v232
	v_max_f32_e32 v233, v39, v39
	v_max_f32_e32 v233, 0, v233
	v_mul_f32_e32 v233, v233, v233
	v_max_f32_e32 v234, v32, v32
	v_max_f32_e32 v234, 0, v234
	v_mul_f32_e32 v234, v234, v234
	v_max_f32_e32 v235, v33, v33
	v_max_f32_e32 v235, 0, v235
	v_mul_f32_e32 v235, v235, v235
	v_max_f32_e32 v236, v34, v34
	v_max_f32_e32 v236, 0, v236
	v_mul_f32_e32 v236, v236, v236
	v_max_f32_e32 v237, v35, v35
	v_max_f32_e32 v237, 0, v237
	v_mul_f32_e32 v237, v237, v237
	v_cvt_pk_bf16_f32 v230, v230, v231
	v_cvt_pk_bf16_f32 v231, v232, v233
	v_cvt_pk_bf16_f32 v234, v234, v235
	v_cvt_pk_bf16_f32 v235, v236, v237
	v_add_co_u32_e32 v246, vcc, 0x120100, v244
	v_addc_co_u32_e32 v247, vcc, 0, v245, vcc
	global_store_dwordx2 v[246:247], v[230:231], off
	global_store_dwordx2 v[246:247], v[234:235], off offset:32
	v_max_f32_e32 v230, v28, v28
	v_max_f32_e32 v230, 0, v230
	v_mul_f32_e32 v230, v230, v230
	v_max_f32_e32 v231, v29, v29
	v_max_f32_e32 v231, 0, v231
	v_mul_f32_e32 v231, v231, v231
	v_max_f32_e32 v232, v30, v30
	v_max_f32_e32 v232, 0, v232
	v_mul_f32_e32 v232, v232, v232
	v_max_f32_e32 v233, v31, v31
	v_max_f32_e32 v233, 0, v233
	v_mul_f32_e32 v233, v233, v233
	v_max_f32_e32 v234, v24, v24
	v_max_f32_e32 v234, 0, v234
	v_mul_f32_e32 v234, v234, v234
	v_max_f32_e32 v235, v25, v25
	v_max_f32_e32 v235, 0, v235
	v_mul_f32_e32 v235, v235, v235
	v_max_f32_e32 v236, v26, v26
	v_max_f32_e32 v236, 0, v236
	v_mul_f32_e32 v236, v236, v236
	v_max_f32_e32 v237, v27, v27
	v_max_f32_e32 v237, 0, v237
	v_mul_f32_e32 v237, v237, v237
	v_cvt_pk_bf16_f32 v230, v230, v231
	v_cvt_pk_bf16_f32 v231, v232, v233
	v_cvt_pk_bf16_f32 v234, v234, v235
	v_cvt_pk_bf16_f32 v235, v236, v237
	v_add_co_u32_e32 v246, vcc, 0x140000, v244
	v_addc_co_u32_e32 v247, vcc, 0, v245, vcc
	global_store_dwordx2 v[246:247], v[230:231], off
	global_store_dwordx2 v[246:247], v[234:235], off offset:32
	v_max_f32_e32 v230, v20, v20
	v_max_f32_e32 v230, 0, v230
	v_mul_f32_e32 v230, v230, v230
	v_max_f32_e32 v231, v21, v21
	v_max_f32_e32 v231, 0, v231
	v_mul_f32_e32 v231, v231, v231
	v_max_f32_e32 v232, v22, v22
	v_max_f32_e32 v232, 0, v232
	v_mul_f32_e32 v232, v232, v232
	v_max_f32_e32 v233, v23, v23
	v_max_f32_e32 v233, 0, v233
	v_mul_f32_e32 v233, v233, v233
	v_max_f32_e32 v234, v16, v16
	v_max_f32_e32 v234, 0, v234
	v_mul_f32_e32 v234, v234, v234
	v_max_f32_e32 v235, v17, v17
	v_max_f32_e32 v235, 0, v235
	v_mul_f32_e32 v235, v235, v235
	v_max_f32_e32 v236, v18, v18
	v_max_f32_e32 v236, 0, v236
	v_mul_f32_e32 v236, v236, v236
	v_max_f32_e32 v237, v19, v19
	v_max_f32_e32 v237, 0, v237
	v_mul_f32_e32 v237, v237, v237
	v_cvt_pk_bf16_f32 v230, v230, v231
	v_cvt_pk_bf16_f32 v231, v232, v233
	v_cvt_pk_bf16_f32 v234, v234, v235
	v_cvt_pk_bf16_f32 v235, v236, v237
	v_add_co_u32_e32 v246, vcc, 0x140100, v244
	v_addc_co_u32_e32 v247, vcc, 0, v245, vcc
	global_store_dwordx2 v[246:247], v[230:231], off
	global_store_dwordx2 v[246:247], v[234:235], off offset:32
	v_max_f32_e32 v230, v12, v12
	v_max_f32_e32 v230, 0, v230
	v_mul_f32_e32 v230, v230, v230
	v_max_f32_e32 v231, v13, v13
	v_max_f32_e32 v231, 0, v231
	v_mul_f32_e32 v231, v231, v231
	v_max_f32_e32 v232, v14, v14
	v_max_f32_e32 v232, 0, v232
	v_mul_f32_e32 v232, v232, v232
	v_max_f32_e32 v233, v15, v15
	v_max_f32_e32 v233, 0, v233
	v_mul_f32_e32 v233, v233, v233
	v_max_f32_e32 v234, v8, v8
	v_max_f32_e32 v234, 0, v234
	v_mul_f32_e32 v234, v234, v234
	v_max_f32_e32 v235, v9, v9
	v_max_f32_e32 v235, 0, v235
	v_mul_f32_e32 v235, v235, v235
	v_max_f32_e32 v236, v10, v10
	v_max_f32_e32 v236, 0, v236
	v_mul_f32_e32 v236, v236, v236
	v_max_f32_e32 v237, v11, v11
	v_max_f32_e32 v237, 0, v237
	v_mul_f32_e32 v237, v237, v237
	v_cvt_pk_bf16_f32 v230, v230, v231
	v_cvt_pk_bf16_f32 v231, v232, v233
	v_cvt_pk_bf16_f32 v234, v234, v235
	v_cvt_pk_bf16_f32 v235, v236, v237
	v_add_co_u32_e32 v246, vcc, 0x160000, v244
	v_addc_co_u32_e32 v247, vcc, 0, v245, vcc
	global_store_dwordx2 v[246:247], v[230:231], off
	global_store_dwordx2 v[246:247], v[234:235], off offset:32
	v_max_f32_e32 v230, v4, v4
	v_max_f32_e32 v230, 0, v230
	v_mul_f32_e32 v230, v230, v230
	v_max_f32_e32 v231, v5, v5
	v_max_f32_e32 v231, 0, v231
	v_mul_f32_e32 v231, v231, v231
	v_max_f32_e32 v232, v6, v6
	v_max_f32_e32 v232, 0, v232
	v_mul_f32_e32 v232, v232, v232
	v_max_f32_e32 v233, v7, v7
	v_max_f32_e32 v233, 0, v233
	v_mul_f32_e32 v233, v233, v233
	v_max_f32_e32 v234, v0, v0
	v_max_f32_e32 v234, 0, v234
	v_mul_f32_e32 v234, v234, v234
	v_max_f32_e32 v235, v1, v1
	v_max_f32_e32 v235, 0, v235
	v_mul_f32_e32 v235, v235, v235
	v_max_f32_e32 v236, v2, v2
	v_max_f32_e32 v236, 0, v236
	v_mul_f32_e32 v236, v236, v236
	v_max_f32_e32 v237, v3, v3
	v_max_f32_e32 v237, 0, v237
	v_mul_f32_e32 v237, v237, v237
	v_cvt_pk_bf16_f32 v230, v230, v231
	v_cvt_pk_bf16_f32 v231, v232, v233
	v_cvt_pk_bf16_f32 v234, v234, v235
	v_cvt_pk_bf16_f32 v235, v236, v237
	v_add_co_u32_e32 v246, vcc, 0x160100, v244
	v_addc_co_u32_e32 v247, vcc, 0, v245, vcc
	global_store_dwordx2 v[246:247], v[230:231], off
	global_store_dwordx2 v[246:247], v[234:235], off offset:32
	s_branch .LBB0_1065
.Lff1_no:
	s_cmp_lt_i32 s79, 22
	s_cbranch_scc1 .Lfb_no
	s_cmp_gt_i32 s79, 24
	s_cbranch_scc1 .Lfb_no
	v_ashrrev_i32_e32 v137, 31, v136
	v_lshl_add_u64 v[140:141], v[142:143], 0, v[136:137]
	v_lshlrev_b64 v[140:141], 1, v[140:141]
	s_cmp_eq_u32 s79, 23
	s_cselect_b32 s2, s34, s40
	s_cselect_b32 s3, s35, s41
	s_cmp_eq_u32 s79, 22
	s_cselect_b32 s2, s38, s2
	s_cselect_b32 s3, s39, s3
	v_lshl_add_u64 v[244:245], s[2:3], 0, v[140:141]
	v_lshl_add_u64 v[246:247], s[36:37], 0, v[140:141]
	s_cbranch_scc1 .Lfb_k0
	v_mov_b32_e32 v236, v244
	v_mov_b32_e32 v237, v245
	global_load_dwordx2 v[194:195], v[236:237], off
	global_load_dwordx2 v[196:197], v[236:237], off offset:32
	v_mov_b32_e32 v236, v246
	v_mov_b32_e32 v237, v247
	global_load_dwordx2 v[198:199], v[236:237], off
	global_load_dwordx2 v[200:201], v[236:237], off offset:32
	s_waitcnt vmcnt(0)
	v_lshlrev_b32_e32 v230, 16, v194
	v_and_b32_e32 v231, 0xffff0000, v194
	v_lshlrev_b32_e32 v232, 16, v195
	v_and_b32_e32 v233, 0xffff0000, v195
	v_lshlrev_b32_e32 v234, 16, v198
	v_and_b32_e32 v235, 0xffff0000, v198
	v_lshlrev_b32_e32 v236, 16, v199
	v_and_b32_e32 v237, 0xffff0000, v199
	v_pk_fma_f32 v[230:231], v[124:125], v[230:231], v[234:235]
	v_pk_fma_f32 v[232:233], v[126:127], v[232:233], v[236:237]
	v_cvt_pk_bf16_f32 v230, v230, v231
	v_cvt_pk_bf16_f32 v231, v232, v233
	v_lshlrev_b32_e32 v194, 16, v196
	v_and_b32_e32 v195, 0xffff0000, v196
	v_lshlrev_b32_e32 v198, 16, v197
	v_and_b32_e32 v199, 0xffff0000, v197
	v_lshlrev_b32_e32 v234, 16, v200
	v_and_b32_e32 v235, 0xffff0000, v200
	v_lshlrev_b32_e32 v236, 16, v201
	v_and_b32_e32 v237, 0xffff0000, v201
	v_pk_fma_f32 v[194:195], v[120:121], v[194:195], v[234:235]
	v_pk_fma_f32 v[198:199], v[122:123], v[198:199], v[236:237]
	v_cvt_pk_bf16_f32 v232, v194, v195
	v_cvt_pk_bf16_f32 v233, v198, v199
	v_mov_b32_e32 v236, v246
	v_mov_b32_e32 v237, v247
	global_store_dwordx2 v[236:237], v[230:231], off
	global_store_dwordx2 v[236:237], v[232:233], off offset:32
	v_add_co_u32_e32 v236, vcc, 0x100, v244
	v_addc_co_u32_e32 v237, vcc, 0, v245, vcc
	global_load_dwordx2 v[194:195], v[236:237], off
	global_load_dwordx2 v[196:197], v[236:237], off offset:32
	v_add_co_u32_e32 v236, vcc, 0x100, v246
	v_addc_co_u32_e32 v237, vcc, 0, v247, vcc
	global_load_dwordx2 v[198:199], v[236:237], off
	global_load_dwordx2 v[200:201], v[236:237], off offset:32
	s_waitcnt vmcnt(0)
	v_lshlrev_b32_e32 v230, 16, v194
	v_and_b32_e32 v231, 0xffff0000, v194
	v_lshlrev_b32_e32 v232, 16, v195
	v_and_b32_e32 v233, 0xffff0000, v195
	v_lshlrev_b32_e32 v234, 16, v198
	v_and_b32_e32 v235, 0xffff0000, v198
	v_lshlrev_b32_e32 v236, 16, v199
	v_and_b32_e32 v237, 0xffff0000, v199
	v_pk_fma_f32 v[230:231], v[116:117], v[230:231], v[234:235]
	v_pk_fma_f32 v[232:233], v[118:119], v[232:233], v[236:237]
	v_cvt_pk_bf16_f32 v230, v230, v231
	v_cvt_pk_bf16_f32 v231, v232, v233
	v_lshlrev_b32_e32 v194, 16, v196
	v_and_b32_e32 v195, 0xffff0000, v196
	v_lshlrev_b32_e32 v198, 16, v197
	v_and_b32_e32 v199, 0xffff0000, v197
	v_lshlrev_b32_e32 v234, 16, v200
	v_and_b32_e32 v235, 0xffff0000, v200
	v_lshlrev_b32_e32 v236, 16, v201
	v_and_b32_e32 v237, 0xffff0000, v201
	v_pk_fma_f32 v[194:195], v[112:113], v[194:195], v[234:235]
	v_pk_fma_f32 v[198:199], v[114:115], v[198:199], v[236:237]
	v_cvt_pk_bf16_f32 v232, v194, v195
	v_cvt_pk_bf16_f32 v233, v198, v199
	v_add_co_u32_e32 v236, vcc, 0x100, v246
	v_addc_co_u32_e32 v237, vcc, 0, v247, vcc
	global_store_dwordx2 v[236:237], v[230:231], off
	global_store_dwordx2 v[236:237], v[232:233], off offset:32
	v_add_co_u32_e32 v236, vcc, 0x8000, v244
	v_addc_co_u32_e32 v237, vcc, 0, v245, vcc
	global_load_dwordx2 v[194:195], v[236:237], off
	global_load_dwordx2 v[196:197], v[236:237], off offset:32
	v_add_co_u32_e32 v236, vcc, 0x8000, v246
	v_addc_co_u32_e32 v237, vcc, 0, v247, vcc
	global_load_dwordx2 v[198:199], v[236:237], off
	global_load_dwordx2 v[200:201], v[236:237], off offset:32
	s_waitcnt vmcnt(0)
	v_lshlrev_b32_e32 v230, 16, v194
	v_and_b32_e32 v231, 0xffff0000, v194
	v_lshlrev_b32_e32 v232, 16, v195
	v_and_b32_e32 v233, 0xffff0000, v195
	v_lshlrev_b32_e32 v234, 16, v198
	v_and_b32_e32 v235, 0xffff0000, v198
	v_lshlrev_b32_e32 v236, 16, v199
	v_and_b32_e32 v237, 0xffff0000, v199
	v_pk_fma_f32 v[230:231], v[108:109], v[230:231], v[234:235]
	v_pk_fma_f32 v[232:233], v[110:111], v[232:233], v[236:237]
	v_cvt_pk_bf16_f32 v230, v230, v231
	v_cvt_pk_bf16_f32 v231, v232, v233
	v_lshlrev_b32_e32 v194, 16, v196
	v_and_b32_e32 v195, 0xffff0000, v196
	v_lshlrev_b32_e32 v198, 16, v197
	v_and_b32_e32 v199, 0xffff0000, v197
	v_lshlrev_b32_e32 v234, 16, v200
	v_and_b32_e32 v235, 0xffff0000, v200
	v_lshlrev_b32_e32 v236, 16, v201
	v_and_b32_e32 v237, 0xffff0000, v201
	v_pk_fma_f32 v[194:195], v[104:105], v[194:195], v[234:235]
	v_pk_fma_f32 v[198:199], v[106:107], v[198:199], v[236:237]
	v_cvt_pk_bf16_f32 v232, v194, v195
	v_cvt_pk_bf16_f32 v233, v198, v199
	v_add_co_u32_e32 v236, vcc, 0x8000, v246
	v_addc_co_u32_e32 v237, vcc, 0, v247, vcc
	global_store_dwordx2 v[236:237], v[230:231], off
	global_store_dwordx2 v[236:237], v[232:233], off offset:32
	v_add_co_u32_e32 v236, vcc, 0x8100, v244
	v_addc_co_u32_e32 v237, vcc, 0, v245, vcc
	global_load_dwordx2 v[194:195], v[236:237], off
	global_load_dwordx2 v[196:197], v[236:237], off offset:32
	v_add_co_u32_e32 v236, vcc, 0x8100, v246
	v_addc_co_u32_e32 v237, vcc, 0, v247, vcc
	global_load_dwordx2 v[198:199], v[236:237], off
	global_load_dwordx2 v[200:201], v[236:237], off offset:32
	s_waitcnt vmcnt(0)
	v_lshlrev_b32_e32 v230, 16, v194
	v_and_b32_e32 v231, 0xffff0000, v194
	v_lshlrev_b32_e32 v232, 16, v195
	v_and_b32_e32 v233, 0xffff0000, v195
	v_lshlrev_b32_e32 v234, 16, v198
	v_and_b32_e32 v235, 0xffff0000, v198
	v_lshlrev_b32_e32 v236, 16, v199
	v_and_b32_e32 v237, 0xffff0000, v199
	v_pk_fma_f32 v[230:231], v[100:101], v[230:231], v[234:235]
	v_pk_fma_f32 v[232:233], v[102:103], v[232:233], v[236:237]
	v_cvt_pk_bf16_f32 v230, v230, v231
	v_cvt_pk_bf16_f32 v231, v232, v233
	v_lshlrev_b32_e32 v194, 16, v196
	v_and_b32_e32 v195, 0xffff0000, v196
	v_lshlrev_b32_e32 v198, 16, v197
	v_and_b32_e32 v199, 0xffff0000, v197
	v_lshlrev_b32_e32 v234, 16, v200
	v_and_b32_e32 v235, 0xffff0000, v200
	v_lshlrev_b32_e32 v236, 16, v201
	v_and_b32_e32 v237, 0xffff0000, v201
	v_pk_fma_f32 v[194:195], v[96:97], v[194:195], v[234:235]
	v_pk_fma_f32 v[198:199], v[98:99], v[198:199], v[236:237]
	v_cvt_pk_bf16_f32 v232, v194, v195
	v_cvt_pk_bf16_f32 v233, v198, v199
	v_add_co_u32_e32 v236, vcc, 0x8100, v246
	v_addc_co_u32_e32 v237, vcc, 0, v247, vcc
	global_store_dwordx2 v[236:237], v[230:231], off
	global_store_dwordx2 v[236:237], v[232:233], off offset:32
	v_add_co_u32_e32 v236, vcc, 0x10000, v244
	v_addc_co_u32_e32 v237, vcc, 0, v245, vcc
	global_load_dwordx2 v[194:195], v[236:237], off
	global_load_dwordx2 v[196:197], v[236:237], off offset:32
	v_add_co_u32_e32 v236, vcc, 0x10000, v246
	v_addc_co_u32_e32 v237, vcc, 0, v247, vcc
	global_load_dwordx2 v[198:199], v[236:237], off
	global_load_dwordx2 v[200:201], v[236:237], off offset:32
	s_waitcnt vmcnt(0)
	v_lshlrev_b32_e32 v230, 16, v194
	v_and_b32_e32 v231, 0xffff0000, v194
	v_lshlrev_b32_e32 v232, 16, v195
	v_and_b32_e32 v233, 0xffff0000, v195
	v_lshlrev_b32_e32 v234, 16, v198
	v_and_b32_e32 v235, 0xffff0000, v198
	v_lshlrev_b32_e32 v236, 16, v199
	v_and_b32_e32 v237, 0xffff0000, v199
	v_pk_fma_f32 v[230:231], v[92:93], v[230:231], v[234:235]
	v_pk_fma_f32 v[232:233], v[94:95], v[232:233], v[236:237]
	v_cvt_pk_bf16_f32 v230, v230, v231
	v_cvt_pk_bf16_f32 v231, v232, v233
	v_lshlrev_b32_e32 v194, 16, v196
	v_and_b32_e32 v195, 0xffff0000, v196
	v_lshlrev_b32_e32 v198, 16, v197
	v_and_b32_e32 v199, 0xffff0000, v197
	v_lshlrev_b32_e32 v234, 16, v200
	v_and_b32_e32 v235, 0xffff0000, v200
	v_lshlrev_b32_e32 v236, 16, v201
	v_and_b32_e32 v237, 0xffff0000, v201
	v_pk_fma_f32 v[194:195], v[88:89], v[194:195], v[234:235]
	v_pk_fma_f32 v[198:199], v[90:91], v[198:199], v[236:237]
	v_cvt_pk_bf16_f32 v232, v194, v195
	v_cvt_pk_bf16_f32 v233, v198, v199
	v_add_co_u32_e32 v236, vcc, 0x10000, v246
	v_addc_co_u32_e32 v237, vcc, 0, v247, vcc
	global_store_dwordx2 v[236:237], v[230:231], off
	global_store_dwordx2 v[236:237], v[232:233], off offset:32
	v_add_co_u32_e32 v236, vcc, 0x10100, v244
	v_addc_co_u32_e32 v237, vcc, 0, v245, vcc
	global_load_dwordx2 v[194:195], v[236:237], off
	global_load_dwordx2 v[196:197], v[236:237], off offset:32
	v_add_co_u32_e32 v236, vcc, 0x10100, v246
	v_addc_co_u32_e32 v237, vcc, 0, v247, vcc
	global_load_dwordx2 v[198:199], v[236:237], off
	global_load_dwordx2 v[200:201], v[236:237], off offset:32
	s_waitcnt vmcnt(0)
	v_lshlrev_b32_e32 v230, 16, v194
	v_and_b32_e32 v231, 0xffff0000, v194
	v_lshlrev_b32_e32 v232, 16, v195
	v_and_b32_e32 v233, 0xffff0000, v195
	v_lshlrev_b32_e32 v234, 16, v198
	v_and_b32_e32 v235, 0xffff0000, v198
	v_lshlrev_b32_e32 v236, 16, v199
	v_and_b32_e32 v237, 0xffff0000, v199
	v_pk_fma_f32 v[230:231], v[84:85], v[230:231], v[234:235]
	v_pk_fma_f32 v[232:233], v[86:87], v[232:233], v[236:237]
	v_cvt_pk_bf16_f32 v230, v230, v231
	v_cvt_pk_bf16_f32 v231, v232, v233
	v_lshlrev_b32_e32 v194, 16, v196
	v_and_b32_e32 v195, 0xffff0000, v196
	v_lshlrev_b32_e32 v198, 16, v197
	v_and_b32_e32 v199, 0xffff0000, v197
	v_lshlrev_b32_e32 v234, 16, v200
	v_and_b32_e32 v235, 0xffff0000, v200
	v_lshlrev_b32_e32 v236, 16, v201
	v_and_b32_e32 v237, 0xffff0000, v201
	v_pk_fma_f32 v[194:195], v[80:81], v[194:195], v[234:235]
	v_pk_fma_f32 v[198:199], v[82:83], v[198:199], v[236:237]
	v_cvt_pk_bf16_f32 v232, v194, v195
	v_cvt_pk_bf16_f32 v233, v198, v199
	v_add_co_u32_e32 v236, vcc, 0x10100, v246
	v_addc_co_u32_e32 v237, vcc, 0, v247, vcc
	global_store_dwordx2 v[236:237], v[230:231], off
	global_store_dwordx2 v[236:237], v[232:233], off offset:32
	v_add_co_u32_e32 v236, vcc, 0x18000, v244
	v_addc_co_u32_e32 v237, vcc, 0, v245, vcc
	global_load_dwordx2 v[194:195], v[236:237], off
	global_load_dwordx2 v[196:197], v[236:237], off offset:32
	v_add_co_u32_e32 v236, vcc, 0x18000, v246
	v_addc_co_u32_e32 v237, vcc, 0, v247, vcc
	global_load_dwordx2 v[198:199], v[236:237], off
	global_load_dwordx2 v[200:201], v[236:237], off offset:32
	s_waitcnt vmcnt(0)
	v_lshlrev_b32_e32 v230, 16, v194
	v_and_b32_e32 v231, 0xffff0000, v194
	v_lshlrev_b32_e32 v232, 16, v195
	v_and_b32_e32 v233, 0xffff0000, v195
	v_lshlrev_b32_e32 v234, 16, v198
	v_and_b32_e32 v235, 0xffff0000, v198
	v_lshlrev_b32_e32 v236, 16, v199
	v_and_b32_e32 v237, 0xffff0000, v199
	v_pk_fma_f32 v[230:231], v[76:77], v[230:231], v[234:235]
	v_pk_fma_f32 v[232:233], v[78:79], v[232:233], v[236:237]
	v_cvt_pk_bf16_f32 v230, v230, v231
	v_cvt_pk_bf16_f32 v231, v232, v233
	v_lshlrev_b32_e32 v194, 16, v196
	v_and_b32_e32 v195, 0xffff0000, v196
	v_lshlrev_b32_e32 v198, 16, v197
	v_and_b32_e32 v199, 0xffff0000, v197
	v_lshlrev_b32_e32 v234, 16, v200
	v_and_b32_e32 v235, 0xffff0000, v200
	v_lshlrev_b32_e32 v236, 16, v201
	v_and_b32_e32 v237, 0xffff0000, v201
	v_pk_fma_f32 v[194:195], v[72:73], v[194:195], v[234:235]
	v_pk_fma_f32 v[198:199], v[74:75], v[198:199], v[236:237]
	v_cvt_pk_bf16_f32 v232, v194, v195
	v_cvt_pk_bf16_f32 v233, v198, v199
	v_add_co_u32_e32 v236, vcc, 0x18000, v246
	v_addc_co_u32_e32 v237, vcc, 0, v247, vcc
	global_store_dwordx2 v[236:237], v[230:231], off
	global_store_dwordx2 v[236:237], v[232:233], off offset:32
	v_add_co_u32_e32 v236, vcc, 0x18100, v244
	v_addc_co_u32_e32 v237, vcc, 0, v245, vcc
	global_load_dwordx2 v[194:195], v[236:237], off
	global_load_dwordx2 v[196:197], v[236:237], off offset:32
	v_add_co_u32_e32 v236, vcc, 0x18100, v246
	v_addc_co_u32_e32 v237, vcc, 0, v247, vcc
	global_load_dwordx2 v[198:199], v[236:237], off
	global_load_dwordx2 v[200:201], v[236:237], off offset:32
	s_waitcnt vmcnt(0)
	v_lshlrev_b32_e32 v230, 16, v194
	v_and_b32_e32 v231, 0xffff0000, v194
	v_lshlrev_b32_e32 v232, 16, v195
	v_and_b32_e32 v233, 0xffff0000, v195
	v_lshlrev_b32_e32 v234, 16, v198
	v_and_b32_e32 v235, 0xffff0000, v198
	v_lshlrev_b32_e32 v236, 16, v199
	v_and_b32_e32 v237, 0xffff0000, v199
	v_pk_fma_f32 v[230:231], v[68:69], v[230:231], v[234:235]
	v_pk_fma_f32 v[232:233], v[70:71], v[232:233], v[236:237]
	v_cvt_pk_bf16_f32 v230, v230, v231
	v_cvt_pk_bf16_f32 v231, v232, v233
	v_lshlrev_b32_e32 v194, 16, v196
	v_and_b32_e32 v195, 0xffff0000, v196
	v_lshlrev_b32_e32 v198, 16, v197
	v_and_b32_e32 v199, 0xffff0000, v197
	v_lshlrev_b32_e32 v234, 16, v200
	v_and_b32_e32 v235, 0xffff0000, v200
	v_lshlrev_b32_e32 v236, 16, v201
	v_and_b32_e32 v237, 0xffff0000, v201
	v_pk_fma_f32 v[194:195], v[64:65], v[194:195], v[234:235]
	v_pk_fma_f32 v[198:199], v[66:67], v[198:199], v[236:237]
	v_cvt_pk_bf16_f32 v232, v194, v195
	v_cvt_pk_bf16_f32 v233, v198, v199
	v_add_co_u32_e32 v236, vcc, 0x18100, v246
	v_addc_co_u32_e32 v237, vcc, 0, v247, vcc
	global_store_dwordx2 v[236:237], v[230:231], off
	global_store_dwordx2 v[236:237], v[232:233], off offset:32
	v_add_co_u32_e32 v236, vcc, 0x40000, v244
	v_addc_co_u32_e32 v237, vcc, 0, v245, vcc
	global_load_dwordx2 v[194:195], v[236:237], off
	global_load_dwordx2 v[196:197], v[236:237], off offset:32
	v_add_co_u32_e32 v236, vcc, 0x40000, v246
	v_addc_co_u32_e32 v237, vcc, 0, v247, vcc
	global_load_dwordx2 v[198:199], v[236:237], off
	global_load_dwordx2 v[200:201], v[236:237], off offset:32
	s_waitcnt vmcnt(0)
	v_lshlrev_b32_e32 v230, 16, v194
	v_and_b32_e32 v231, 0xffff0000, v194
	v_lshlrev_b32_e32 v232, 16, v195
	v_and_b32_e32 v233, 0xffff0000, v195
	v_lshlrev_b32_e32 v234, 16, v198
	v_and_b32_e32 v235, 0xffff0000, v198
	v_lshlrev_b32_e32 v236, 16, v199
	v_and_b32_e32 v237, 0xffff0000, v199
	v_pk_fma_f32 v[230:231], v[60:61], v[230:231], v[234:235]
	v_pk_fma_f32 v[232:233], v[62:63], v[232:233], v[236:237]
	v_cvt_pk_bf16_f32 v230, v230, v231
	v_cvt_pk_bf16_f32 v231, v232, v233
	v_lshlrev_b32_e32 v194, 16, v196
	v_and_b32_e32 v195, 0xffff0000, v196
	v_lshlrev_b32_e32 v198, 16, v197
	v_and_b32_e32 v199, 0xffff0000, v197
	v_lshlrev_b32_e32 v234, 16, v200
	v_and_b32_e32 v235, 0xffff0000, v200
	v_lshlrev_b32_e32 v236, 16, v201
	v_and_b32_e32 v237, 0xffff0000, v201
	v_pk_fma_f32 v[194:195], v[56:57], v[194:195], v[234:235]
	v_pk_fma_f32 v[198:199], v[58:59], v[198:199], v[236:237]
	v_cvt_pk_bf16_f32 v232, v194, v195
	v_cvt_pk_bf16_f32 v233, v198, v199
	v_add_co_u32_e32 v236, vcc, 0x40000, v246
	v_addc_co_u32_e32 v237, vcc, 0, v247, vcc
	global_store_dwordx2 v[236:237], v[230:231], off
	global_store_dwordx2 v[236:237], v[232:233], off offset:32
	v_add_co_u32_e32 v236, vcc, 0x40100, v244
	v_addc_co_u32_e32 v237, vcc, 0, v245, vcc
	global_load_dwordx2 v[194:195], v[236:237], off
	global_load_dwordx2 v[196:197], v[236:237], off offset:32
	v_add_co_u32_e32 v236, vcc, 0x40100, v246
	v_addc_co_u32_e32 v237, vcc, 0, v247, vcc
	global_load_dwordx2 v[198:199], v[236:237], off
	global_load_dwordx2 v[200:201], v[236:237], off offset:32
	s_waitcnt vmcnt(0)
	v_lshlrev_b32_e32 v230, 16, v194
	v_and_b32_e32 v231, 0xffff0000, v194
	v_lshlrev_b32_e32 v232, 16, v195
	v_and_b32_e32 v233, 0xffff0000, v195
	v_lshlrev_b32_e32 v234, 16, v198
	v_and_b32_e32 v235, 0xffff0000, v198
	v_lshlrev_b32_e32 v236, 16, v199
	v_and_b32_e32 v237, 0xffff0000, v199
	v_pk_fma_f32 v[230:231], v[52:53], v[230:231], v[234:235]
	v_pk_fma_f32 v[232:233], v[54:55], v[232:233], v[236:237]
	v_cvt_pk_bf16_f32 v230, v230, v231
	v_cvt_pk_bf16_f32 v231, v232, v233
	v_lshlrev_b32_e32 v194, 16, v196
	v_and_b32_e32 v195, 0xffff0000, v196
	v_lshlrev_b32_e32 v198, 16, v197
	v_and_b32_e32 v199, 0xffff0000, v197
	v_lshlrev_b32_e32 v234, 16, v200
	v_and_b32_e32 v235, 0xffff0000, v200
	v_lshlrev_b32_e32 v236, 16, v201
	v_and_b32_e32 v237, 0xffff0000, v201
	v_pk_fma_f32 v[194:195], v[48:49], v[194:195], v[234:235]
	v_pk_fma_f32 v[198:199], v[50:51], v[198:199], v[236:237]
	v_cvt_pk_bf16_f32 v232, v194, v195
	v_cvt_pk_bf16_f32 v233, v198, v199
	v_add_co_u32_e32 v236, vcc, 0x40100, v246
	v_addc_co_u32_e32 v237, vcc, 0, v247, vcc
	global_store_dwordx2 v[236:237], v[230:231], off
	global_store_dwordx2 v[236:237], v[232:233], off offset:32
	v_add_co_u32_e32 v236, vcc, 0x48000, v244
	v_addc_co_u32_e32 v237, vcc, 0, v245, vcc
	global_load_dwordx2 v[194:195], v[236:237], off
	global_load_dwordx2 v[196:197], v[236:237], off offset:32
	v_add_co_u32_e32 v236, vcc, 0x48000, v246
	v_addc_co_u32_e32 v237, vcc, 0, v247, vcc
	global_load_dwordx2 v[198:199], v[236:237], off
	global_load_dwordx2 v[200:201], v[236:237], off offset:32
	s_waitcnt vmcnt(0)
	v_lshlrev_b32_e32 v230, 16, v194
	v_and_b32_e32 v231, 0xffff0000, v194
	v_lshlrev_b32_e32 v232, 16, v195
	v_and_b32_e32 v233, 0xffff0000, v195
	v_lshlrev_b32_e32 v234, 16, v198
	v_and_b32_e32 v235, 0xffff0000, v198
	v_lshlrev_b32_e32 v236, 16, v199
	v_and_b32_e32 v237, 0xffff0000, v199
	v_pk_fma_f32 v[230:231], v[44:45], v[230:231], v[234:235]
	v_pk_fma_f32 v[232:233], v[46:47], v[232:233], v[236:237]
	v_cvt_pk_bf16_f32 v230, v230, v231
	v_cvt_pk_bf16_f32 v231, v232, v233
	v_lshlrev_b32_e32 v194, 16, v196
	v_and_b32_e32 v195, 0xffff0000, v196
	v_lshlrev_b32_e32 v198, 16, v197
	v_and_b32_e32 v199, 0xffff0000, v197
	v_lshlrev_b32_e32 v234, 16, v200
	v_and_b32_e32 v235, 0xffff0000, v200
	v_lshlrev_b32_e32 v236, 16, v201
	v_and_b32_e32 v237, 0xffff0000, v201
	v_pk_fma_f32 v[194:195], v[40:41], v[194:195], v[234:235]
	v_pk_fma_f32 v[198:199], v[42:43], v[198:199], v[236:237]
	v_cvt_pk_bf16_f32 v232, v194, v195
	v_cvt_pk_bf16_f32 v233, v198, v199
	v_add_co_u32_e32 v236, vcc, 0x48000, v246
	v_addc_co_u32_e32 v237, vcc, 0, v247, vcc
	global_store_dwordx2 v[236:237], v[230:231], off
	global_store_dwordx2 v[236:237], v[232:233], off offset:32
	v_add_co_u32_e32 v236, vcc, 0x48100, v244
	v_addc_co_u32_e32 v237, vcc, 0, v245, vcc
	global_load_dwordx2 v[194:195], v[236:237], off
	global_load_dwordx2 v[196:197], v[236:237], off offset:32
	v_add_co_u32_e32 v236, vcc, 0x48100, v246
	v_addc_co_u32_e32 v237, vcc, 0, v247, vcc
	global_load_dwordx2 v[198:199], v[236:237], off
	global_load_dwordx2 v[200:201], v[236:237], off offset:32
	s_waitcnt vmcnt(0)
	v_lshlrev_b32_e32 v230, 16, v194
	v_and_b32_e32 v231, 0xffff0000, v194
	v_lshlrev_b32_e32 v232, 16, v195
	v_and_b32_e32 v233, 0xffff0000, v195
	v_lshlrev_b32_e32 v234, 16, v198
	v_and_b32_e32 v235, 0xffff0000, v198
	v_lshlrev_b32_e32 v236, 16, v199
	v_and_b32_e32 v237, 0xffff0000, v199
	v_pk_fma_f32 v[230:231], v[36:37], v[230:231], v[234:235]
	v_pk_fma_f32 v[232:233], v[38:39], v[232:233], v[236:237]
	v_cvt_pk_bf16_f32 v230, v230, v231
	v_cvt_pk_bf16_f32 v231, v232, v233
	v_lshlrev_b32_e32 v194, 16, v196
	v_and_b32_e32 v195, 0xffff0000, v196
	v_lshlrev_b32_e32 v198, 16, v197
	v_and_b32_e32 v199, 0xffff0000, v197
	v_lshlrev_b32_e32 v234, 16, v200
	v_and_b32_e32 v235, 0xffff0000, v200
	v_lshlrev_b32_e32 v236, 16, v201
	v_and_b32_e32 v237, 0xffff0000, v201
	v_pk_fma_f32 v[194:195], v[32:33], v[194:195], v[234:235]
	v_pk_fma_f32 v[198:199], v[34:35], v[198:199], v[236:237]
	v_cvt_pk_bf16_f32 v232, v194, v195
	v_cvt_pk_bf16_f32 v233, v198, v199
	v_add_co_u32_e32 v236, vcc, 0x48100, v246
	v_addc_co_u32_e32 v237, vcc, 0, v247, vcc
	global_store_dwordx2 v[236:237], v[230:231], off
	global_store_dwordx2 v[236:237], v[232:233], off offset:32
	v_add_co_u32_e32 v236, vcc, 0x50000, v244
	v_addc_co_u32_e32 v237, vcc, 0, v245, vcc
	global_load_dwordx2 v[194:195], v[236:237], off
	global_load_dwordx2 v[196:197], v[236:237], off offset:32
	v_add_co_u32_e32 v236, vcc, 0x50000, v246
	v_addc_co_u32_e32 v237, vcc, 0, v247, vcc
	global_load_dwordx2 v[198:199], v[236:237], off
	global_load_dwordx2 v[200:201], v[236:237], off offset:32
	s_waitcnt vmcnt(0)
	v_lshlrev_b32_e32 v230, 16, v194
	v_and_b32_e32 v231, 0xffff0000, v194
	v_lshlrev_b32_e32 v232, 16, v195
	v_and_b32_e32 v233, 0xffff0000, v195
	v_lshlrev_b32_e32 v234, 16, v198
	v_and_b32_e32 v235, 0xffff0000, v198
	v_lshlrev_b32_e32 v236, 16, v199
	v_and_b32_e32 v237, 0xffff0000, v199
	v_pk_fma_f32 v[230:231], v[28:29], v[230:231], v[234:235]
	v_pk_fma_f32 v[232:233], v[30:31], v[232:233], v[236:237]
	v_cvt_pk_bf16_f32 v230, v230, v231
	v_cvt_pk_bf16_f32 v231, v232, v233
	v_lshlrev_b32_e32 v194, 16, v196
	v_and_b32_e32 v195, 0xffff0000, v196
	v_lshlrev_b32_e32 v198, 16, v197
	v_and_b32_e32 v199, 0xffff0000, v197
	v_lshlrev_b32_e32 v234, 16, v200
	v_and_b32_e32 v235, 0xffff0000, v200
	v_lshlrev_b32_e32 v236, 16, v201
	v_and_b32_e32 v237, 0xffff0000, v201
	v_pk_fma_f32 v[194:195], v[24:25], v[194:195], v[234:235]
	v_pk_fma_f32 v[198:199], v[26:27], v[198:199], v[236:237]
	v_cvt_pk_bf16_f32 v232, v194, v195
	v_cvt_pk_bf16_f32 v233, v198, v199
	v_add_co_u32_e32 v236, vcc, 0x50000, v246
	v_addc_co_u32_e32 v237, vcc, 0, v247, vcc
	global_store_dwordx2 v[236:237], v[230:231], off
	global_store_dwordx2 v[236:237], v[232:233], off offset:32
	v_add_co_u32_e32 v236, vcc, 0x50100, v244
	v_addc_co_u32_e32 v237, vcc, 0, v245, vcc
	global_load_dwordx2 v[194:195], v[236:237], off
	global_load_dwordx2 v[196:197], v[236:237], off offset:32
	v_add_co_u32_e32 v236, vcc, 0x50100, v246
	v_addc_co_u32_e32 v237, vcc, 0, v247, vcc
	global_load_dwordx2 v[198:199], v[236:237], off
	global_load_dwordx2 v[200:201], v[236:237], off offset:32
	s_waitcnt vmcnt(0)
	v_lshlrev_b32_e32 v230, 16, v194
	v_and_b32_e32 v231, 0xffff0000, v194
	v_lshlrev_b32_e32 v232, 16, v195
	v_and_b32_e32 v233, 0xffff0000, v195
	v_lshlrev_b32_e32 v234, 16, v198
	v_and_b32_e32 v235, 0xffff0000, v198
	v_lshlrev_b32_e32 v236, 16, v199
	v_and_b32_e32 v237, 0xffff0000, v199
	v_pk_fma_f32 v[230:231], v[20:21], v[230:231], v[234:235]
	v_pk_fma_f32 v[232:233], v[22:23], v[232:233], v[236:237]
	v_cvt_pk_bf16_f32 v230, v230, v231
	v_cvt_pk_bf16_f32 v231, v232, v233
	v_lshlrev_b32_e32 v194, 16, v196
	v_and_b32_e32 v195, 0xffff0000, v196
	v_lshlrev_b32_e32 v198, 16, v197
	v_and_b32_e32 v199, 0xffff0000, v197
	v_lshlrev_b32_e32 v234, 16, v200
	v_and_b32_e32 v235, 0xffff0000, v200
	v_lshlrev_b32_e32 v236, 16, v201
	v_and_b32_e32 v237, 0xffff0000, v201
	v_pk_fma_f32 v[194:195], v[16:17], v[194:195], v[234:235]
	v_pk_fma_f32 v[198:199], v[18:19], v[198:199], v[236:237]
	v_cvt_pk_bf16_f32 v232, v194, v195
	v_cvt_pk_bf16_f32 v233, v198, v199
	v_add_co_u32_e32 v236, vcc, 0x50100, v246
	v_addc_co_u32_e32 v237, vcc, 0, v247, vcc
	global_store_dwordx2 v[236:237], v[230:231], off
	global_store_dwordx2 v[236:237], v[232:233], off offset:32
	v_add_co_u32_e32 v236, vcc, 0x58000, v244
	v_addc_co_u32_e32 v237, vcc, 0, v245, vcc
	global_load_dwordx2 v[194:195], v[236:237], off
	global_load_dwordx2 v[196:197], v[236:237], off offset:32
	v_add_co_u32_e32 v236, vcc, 0x58000, v246
	v_addc_co_u32_e32 v237, vcc, 0, v247, vcc
	global_load_dwordx2 v[198:199], v[236:237], off
	global_load_dwordx2 v[200:201], v[236:237], off offset:32
	s_waitcnt vmcnt(0)
	v_lshlrev_b32_e32 v230, 16, v194
	v_and_b32_e32 v231, 0xffff0000, v194
	v_lshlrev_b32_e32 v232, 16, v195
	v_and_b32_e32 v233, 0xffff0000, v195
	v_lshlrev_b32_e32 v234, 16, v198
	v_and_b32_e32 v235, 0xffff0000, v198
	v_lshlrev_b32_e32 v236, 16, v199
	v_and_b32_e32 v237, 0xffff0000, v199
	v_pk_fma_f32 v[230:231], v[12:13], v[230:231], v[234:235]
	v_pk_fma_f32 v[232:233], v[14:15], v[232:233], v[236:237]
	v_cvt_pk_bf16_f32 v230, v230, v231
	v_cvt_pk_bf16_f32 v231, v232, v233
	v_lshlrev_b32_e32 v194, 16, v196
	v_and_b32_e32 v195, 0xffff0000, v196
	v_lshlrev_b32_e32 v198, 16, v197
	v_and_b32_e32 v199, 0xffff0000, v197
	v_lshlrev_b32_e32 v234, 16, v200
	v_and_b32_e32 v235, 0xffff0000, v200
	v_lshlrev_b32_e32 v236, 16, v201
	v_and_b32_e32 v237, 0xffff0000, v201
	v_pk_fma_f32 v[194:195], v[8:9], v[194:195], v[234:235]
	v_pk_fma_f32 v[198:199], v[10:11], v[198:199], v[236:237]
	v_cvt_pk_bf16_f32 v232, v194, v195
	v_cvt_pk_bf16_f32 v233, v198, v199
	v_add_co_u32_e32 v236, vcc, 0x58000, v246
	v_addc_co_u32_e32 v237, vcc, 0, v247, vcc
	global_store_dwordx2 v[236:237], v[230:231], off
	global_store_dwordx2 v[236:237], v[232:233], off offset:32
	v_add_co_u32_e32 v236, vcc, 0x58100, v244
	v_addc_co_u32_e32 v237, vcc, 0, v245, vcc
	global_load_dwordx2 v[194:195], v[236:237], off
	global_load_dwordx2 v[196:197], v[236:237], off offset:32
	v_add_co_u32_e32 v236, vcc, 0x58100, v246
	v_addc_co_u32_e32 v237, vcc, 0, v247, vcc
	global_load_dwordx2 v[198:199], v[236:237], off
	global_load_dwordx2 v[200:201], v[236:237], off offset:32
	s_waitcnt vmcnt(0)
	v_lshlrev_b32_e32 v230, 16, v194
	v_and_b32_e32 v231, 0xffff0000, v194
	v_lshlrev_b32_e32 v232, 16, v195
	v_and_b32_e32 v233, 0xffff0000, v195
	v_lshlrev_b32_e32 v234, 16, v198
	v_and_b32_e32 v235, 0xffff0000, v198
	v_lshlrev_b32_e32 v236, 16, v199
	v_and_b32_e32 v237, 0xffff0000, v199
	v_pk_fma_f32 v[230:231], v[4:5], v[230:231], v[234:235]
	v_pk_fma_f32 v[232:233], v[6:7], v[232:233], v[236:237]
	v_cvt_pk_bf16_f32 v230, v230, v231
	v_cvt_pk_bf16_f32 v231, v232, v233
	v_lshlrev_b32_e32 v194, 16, v196
	v_and_b32_e32 v195, 0xffff0000, v196
	v_lshlrev_b32_e32 v198, 16, v197
	v_and_b32_e32 v199, 0xffff0000, v197
	v_lshlrev_b32_e32 v234, 16, v200
	v_and_b32_e32 v235, 0xffff0000, v200
	v_lshlrev_b32_e32 v236, 16, v201
	v_and_b32_e32 v237, 0xffff0000, v201
	v_pk_fma_f32 v[194:195], v[0:1], v[194:195], v[234:235]
	v_pk_fma_f32 v[198:199], v[2:3], v[198:199], v[236:237]
	v_cvt_pk_bf16_f32 v232, v194, v195
	v_cvt_pk_bf16_f32 v233, v198, v199
	v_add_co_u32_e32 v236, vcc, 0x58100, v246
	v_addc_co_u32_e32 v237, vcc, 0, v247, vcc
	global_store_dwordx2 v[236:237], v[230:231], off
	global_store_dwordx2 v[236:237], v[232:233], off offset:32
	s_branch .LBB0_1065
